# MLA: softmax reference folded into the first QK MFMA's C operand (no per-score subtraction); 6 V-fragment buffers
# speedup vs baseline: 1.0131x; 1.0114x over previous
; #define LAS __attribute__((address_space(3)))
; DI void mla_load(const bf16_t* KNOPE, const bf16_t* KROPE, const bf16_t* VT, int h, size_t tokb, int kt, u32x4 (&r)[5], int tid) {
; #pragma unroll
;     for (int i = 0; i < 2; ++i) { const int q = tid + 512 * i, key = q >> 4, ch = q & 15;
;         r[i] = *(const u32x4*)(KNOPE + (tokb + kt * 64 + key) * 1024 + h * 128 + 8 * ch); }
;     { const int key = tid >> 3, ch = tid & 7; r[2] = *(const u32x4*)(KROPE + (tokb + kt * 64 + key) * 64 + 8 * ch); }
; #pragma unroll
;     for (int i = 0; i < 2; ++i) { const int q = tid + 512 * i, d = q >> 3, ch = q & 7;
;         r[3 + i] = *(const u32x4*)(VT + (size_t)(h * 128 + d) * T_ + tokb + kt * 64 + 8 * ch); }
; }
; DI void mla_store(LAS unsigned char* buf, const u32x4 (&r)[5], int tid) {
; #pragma unroll
;     for (int i = 0; i < 2; ++i) { const int q = tid + 512 * i, key = q >> 4, ch = q & 15; *(LAS u32x4*)(buf + key * 400 + ch * 16) = r[i]; }
;     { const int key = tid >> 3, ch = tid & 7; *(LAS u32x4*)(buf + key * 400 + 256 + ch * 16) = r[2]; }
; #pragma unroll
;     for (int i = 0; i < 2; ++i) { const int q = tid + 512 * i, d = q >> 3, ch = q & 7; LAS unsigned char* vp = buf + 25600 + d * 136 + ch * 16;
;         *(LAS u32x2*)vp = (u32x2){r[3 + i].x, r[3 + i].y}; *(LAS u32x2*)(vp + 8) = (u32x2){r[3 + i].z, r[3 + i].w}; }
; }
; DI void mla_unit(const Params& p, LAS unsigned char* lds, int b, int h, int qb, int tid) {
;     ...
;     const int lane = tid & 63, w = __builtin_amdgcn_readfirstlane(tid >> 6), c = lane & 31, hi = lane >> 5;
;     const int q0 = qb * 256, qw0 = q0 + 32 * w, qpos = qw0 + c;
;     const size_t tokb = (size_t)b * S_;
;     bf16x8 qf[12];
;     { const bf16_t* qp = QMLA + (tokb + qpos) * 1536 + h * 192 + 8 * hi;
; #pragma unroll
;       for (int st = 0; st < 12; ++st) qf[st] = *(const bf16x8*)(qp + 16 * st); }
;     f32x16 o[4];
; #pragma unroll
;     for (int db = 0; db < 4; ++db)
; #pragma unroll
;         for (int i = 0; i < 16; ++i) o[db][i] = 0.f;
;     float m = -1e20f, l = 0.f;
;     const int nkt = 4 * qb + 4;
;     u32x4 r[5];
;     __syncthreads();
;     mla_load(KNOPE, KROPE, VT, h, tokb, 0, r, tid); mla_store(lds, r, tid);
;     __syncthreads();
.LBB0_618:
	s_or_b64 exec, exec, s[2:3]
	v_mov_b32_e32 v1, s1
	s_waitcnt lgkmcnt(0)
	s_barrier
	ds_read_b32 v1, v1
	s_movk_i32 s2, 0x7f
	s_waitcnt lgkmcnt(0)
	v_cmp_lt_i32_e32 vcc, s2, v1
	v_readfirstlane_b32 s4, v1
	s_mov_b64 s[2:3], -1
	s_cbranch_vccnz .LBB0_613
	s_not_b32 s2, s4
	s_bfe_u32 s8, s2, 0x50001
	s_ashr_i32 s2, s4, 5
	s_and_b32 s2, s2, -2
	s_and_b32 s3, s4, 1
	s_or_b32 s2, s2, s3
	v_readfirstlane_b32 s3, v0
	s_ashr_i32 s3, s3, 1
	s_lshl_b32 s79, s8, 8
	s_and_b32 s58, s3, 0xffffffe0
	v_and_b32_e32 v1, 31, v0
	s_add_i32 s58, s58, s79
	v_or_b32_e32 v2, s58, v1
	s_ashr_i32 s3, s2, 31
	s_lshl_b64 s[4:5], s[2:3], 13
	v_ashrrev_i32_e32 v3, 31, v2
	v_lshl_add_u64 v[150:151], s[4:5], 0, v[2:3]
	v_mov_b64_e32 v[4:5], s[70:71]
	v_add_u32_e32 v17, 0x200, v0
	v_bfe_u32 v16, v0, 5, 1
	v_mad_u64_u32 v[4:5], s[6:7], v150, s12, v[4:5]
	v_ashrrev_i32_e32 v6, 4, v0
	v_ashrrev_i32_e32 v10, 4, v17
	v_mad_i32_i24 v5, v151, s12, v5
	v_lshlrev_b32_e32 v148, 4, v16
	v_lshlrev_b32_e32 v3, 4, v0
	v_ashrrev_i32_e32 v7, 31, v6
	v_ashrrev_i32_e32 v11, 31, v10
	v_lshl_add_u64 v[4:5], v[4:5], 0, v[148:149]
	v_and_b32_e32 v152, 0xf0, v3
	v_mov_b32_e32 v153, v149
	v_lshl_add_u64 v[8:9], s[4:5], 0, v[6:7]
	v_lshl_add_u64 v[12:13], s[4:5], 0, v[10:11]
	global_load_dwordx4 v[80:83], v[4:5], off
	global_load_dwordx4 v[84:87], v[4:5], off offset:32
	global_load_dwordx4 v[88:91], v[4:5], off offset:64
	global_load_dwordx4 v[92:95], v[4:5], off offset:96
	global_load_dwordx4 v[96:99], v[4:5], off offset:128
	global_load_dwordx4 v[100:103], v[4:5], off offset:160
	global_load_dwordx4 v[104:107], v[4:5], off offset:192
	global_load_dwordx4 v[108:111], v[4:5], off offset:224
	global_load_dwordx4 v[112:115], v[4:5], off offset:256
	global_load_dwordx4 v[116:119], v[4:5], off offset:288
	global_load_dwordx4 v[120:123], v[4:5], off offset:320
	global_load_dwordx4 v[124:127], v[4:5], off offset:352
	v_lshl_add_u64 v[4:5], s[72:73], 0, v[152:153]
	v_lshlrev_b64 v[8:9], 11, v[8:9]
	v_lshlrev_b64 v[12:13], 11, v[12:13]
	v_lshl_add_u64 v[8:9], v[4:5], 0, v[8:9]
	v_lshl_add_u64 v[4:5], v[4:5], 0, v[12:13]
	s_barrier
	global_load_dwordx4 v[128:131], v[8:9], off
	global_load_dwordx4 v[132:135], v[4:5], off
	v_ashrrev_i32_e32 v4, 3, v0
	s_lshl_b32 s59, s8, 2
	v_ashrrev_i32_e32 v5, 31, v4
	s_add_i32 s59, s59, 4
	v_lshl_add_u64 v[8:9], s[4:5], 0, v[4:5]
	s_lshl_b64 s[4:5], s[2:3], 14
	v_lshlrev_b64 v[8:9], 7, v[8:9]
	s_add_u32 s6, s52, s4
	v_add_u32_e32 v14, s42, v4
	v_lshl_add_u64 v[8:9], s[54:55], 0, v[8:9]
	v_and_b32_e32 v154, 0x70, v3
	v_mov_b32_e32 v155, v149
	s_addc_u32 s7, s53, s5
	v_ashrrev_i32_e32 v15, 31, v14
	v_lshl_add_u64 v[8:9], v[8:9], 0, v[154:155]
	v_lshl_add_u64 v[12:13], s[6:7], 0, v[154:155]
	v_lshlrev_b64 v[14:15], 16, v[14:15]
	v_lshl_add_u64 v[14:15], v[12:13], 0, v[14:15]
	global_load_dwordx4 v[136:139], v[8:9], off
	global_load_dwordx4 v[140:143], v[14:15], off
	v_ashrrev_i32_e32 v8, 3, v17
	v_add_u32_e32 v14, s42, v8
	v_ashrrev_i32_e32 v15, 31, v14
	v_lshlrev_b64 v[14:15], 16, v[14:15]
	v_lshl_add_u64 v[12:13], v[12:13], 0, v[14:15]
	global_load_dwordx4 v[144:147], v[12:13], off
	v_mul_lo_u32 v171, v6, s13
	v_add_u32_e32 v3, 0, v152
	v_mul_lo_u32 v173, v10, s13
	v_add_u32_e32 v9, v3, v171
	v_add_u32_e32 v3, v3, v173
	v_mul_lo_u32 v172, v4, s13
	v_mul_lo_u32 v175, v4, s33
	v_mul_lo_u32 v176, v8, s33
	s_or_b32 s78, s58, 31
	v_lshlrev_b32_e32 v174, 2, v16
	s_add_u32 s4, s4, s43
	v_sub_u32_e32 v179, v2, v174
	s_addc_u32 s5, s5, s48
	v_and_b32_e32 v0, 15, v0
	v_mul_u32_u24_e32 v177, 0x88, v1
	v_mul_u32_u24_e32 v178, 0x190, v1
	v_lshlrev_b32_e32 v0, 4, v0
	v_mov_b32_e32 v1, v149
	v_mov_b32_e32 v14, v149
	v_mov_b32_e32 v15, v149
	v_lshlrev_b32_e32 v153, 3, v16
	v_mov_b32_e32 v12, v149
	v_mov_b32_e32 v13, v149
	s_mov_b32 s80, 0
	v_mov_b32_e32 v180, 0xe0ad78ec
	v_mov_b32_e32 v240, 0
	v_mov_b32_e32 v241, 0
	v_mov_b32_e32 v242, 0
	v_mov_b32_e32 v243, 0
	v_mov_b32_e32 v244, 0
	v_mov_b32_e32 v245, 0
	v_mov_b32_e32 v246, 0
	v_mov_b32_e32 v247, 0
	v_mov_b32_e32 v248, 0
	v_mov_b32_e32 v249, 0
	v_mov_b32_e32 v250, 0
	v_mov_b32_e32 v251, 0
	v_mov_b32_e32 v252, 0
	v_mov_b32_e32 v253, 0
	v_mov_b32_e32 v254, 0
	v_mov_b32_e32 v255, 0
	s_waitcnt vmcnt(4)
	ds_write_b128 v9, v[128:131]
	s_waitcnt vmcnt(3)
	ds_write_b128 v3, v[132:135]
	v_add_u32_e32 v3, 0, v154
	v_add_u32_e32 v9, v3, v172
	s_waitcnt vmcnt(2)
	ds_write_b128 v9, v[136:139] offset:256
	v_add3_u32 v9, v3, v175, s40
	v_add3_u32 v3, v3, v176, s40
	s_waitcnt vmcnt(1)
	ds_write2_b64 v9, v[140:141], v[142:143] offset1:1
	v_ashrrev_i32_e32 v9, 31, v8
	s_waitcnt vmcnt(0)
	ds_write2_b64 v3, v[144:145], v[146:147] offset1:1
	v_lshlrev_b64 v[2:3], 16, v[4:5]
	v_lshl_add_u64 v[2:3], s[4:5], 0, v[2:3]
	v_lshl_add_u64 v[156:157], v[2:3], 0, v[154:155]
	v_lshlrev_b64 v[2:3], 16, v[8:9]
	v_lshl_add_u64 v[2:3], s[4:5], 0, v[2:3]
	s_lshl_b64 s[4:5], s[2:3], 20
	s_add_u32 s4, s4, 0x2f002000
	s_addc_u32 s5, s5, 0
	s_lshl_b64 s[2:3], s[2:3], 24
	v_lshl_add_u64 v[158:159], v[2:3], 0, v[154:155]
	v_lshlrev_b64 v[2:3], 7, v[4:5]
	s_add_u32 s2, s49, s2
	v_lshl_add_u64 v[160:161], s[4:5], 0, v[2:3]
	s_addc_u32 s3, 0, s3
	v_lshlrev_b64 v[2:3], 11, v[10:11]
	v_lshl_add_u64 v[2:3], s[2:3], 0, v[2:3]
	v_lshl_add_u64 v[162:163], v[2:3], 0, v[0:1]
	v_lshlrev_b64 v[2:3], 11, v[6:7]
	v_lshl_add_u64 v[2:3], s[2:3], 0, v[2:3]
	v_lshl_add_u64 v[164:165], v[2:3], 0, v[0:1]
	v_mov_b32_e32 v0, v149
	v_mov_b32_e32 v2, v149
	v_mov_b32_e32 v3, v149
	v_mov_b32_e32 v4, v149
	v_mov_b32_e32 v5, v149
	v_mov_b32_e32 v6, v149
	v_mov_b32_e32 v7, v149
	v_mov_b32_e32 v8, v149
	v_mov_b32_e32 v9, v149
	v_mov_b32_e32 v10, v149
	v_mov_b32_e32 v11, v149
	v_mov_b64_e32 v[30:31], v[14:15]
	v_mov_b64_e32 v[46:47], v[14:15]
	v_mov_b64_e32 v[62:63], v[14:15]
	v_or_b32_e32 v160, v160, v154
	s_addk_i32 s79, 0x100
	v_mov_b32_e32 v155, 0
	v_mov_b64_e32 v[28:29], v[12:13]
	v_mov_b64_e32 v[26:27], v[10:11]
	v_mov_b64_e32 v[24:25], v[8:9]
	v_mov_b64_e32 v[22:23], v[6:7]
	v_mov_b64_e32 v[20:21], v[4:5]
	v_mov_b64_e32 v[18:19], v[2:3]
	v_mov_b64_e32 v[16:17], v[0:1]
	v_mov_b64_e32 v[44:45], v[12:13]
	v_mov_b64_e32 v[42:43], v[10:11]
	v_mov_b64_e32 v[40:41], v[8:9]
	v_mov_b64_e32 v[38:39], v[6:7]
	v_mov_b64_e32 v[36:37], v[4:5]
	v_mov_b64_e32 v[34:35], v[2:3]
	v_mov_b64_e32 v[32:33], v[0:1]
	v_mov_b64_e32 v[60:61], v[12:13]
	v_mov_b64_e32 v[58:59], v[10:11]
	v_mov_b64_e32 v[56:57], v[8:9]
	v_mov_b64_e32 v[54:55], v[6:7]
	v_mov_b64_e32 v[52:53], v[4:5]
	v_mov_b64_e32 v[50:51], v[2:3]
	v_mov_b64_e32 v[48:49], v[0:1]
	s_mov_b32 s2, 0
	s_waitcnt lgkmcnt(0)
	s_barrier

; #define LAS __attribute__((address_space(3)))
; DI float xhalf_max(float v) { unsigned a = __builtin_bit_cast(unsigned, v), b = a; swap32(a, b); return fmaxf(__builtin_bit_cast(float, a), __builtin_bit_cast(float, b)); }
; DI float fexp2(float x) { return __builtin_amdgcn_exp2f(x); }
; #define MFMA32(a, b, c) __builtin_amdgcn_mfma_f32_32x32x16_bf16((a), (b), (c), 0, 0, 0)
; DI void mla_unit(const Params& p, LAS unsigned char* lds, int b, int h, int qb, int tid) {
;     ...
;         LAS const unsigned char* buf = lds + (kt & 1) * MLA_BUF;
;         if (kt * 64 <= qw0 + 31) {
; #pragma unroll
;             for (int sub = 0; sub < 2; ++sub) {
;                 const int kbase = kt * 64 + 32 * sub;
;                 f32x16 s;
; #pragma unroll
;                 for (int i = 0; i < 16; ++i) s[i] = 0.f;
; #pragma unroll
;                 for (int st = 0; st < 12; ++st) {
;                     const bf16x8 a = *(LAS const bf16x8*)(buf + (32 * sub + c) * 400 + st * 32 + hi * 16);
;                     s = MFMA32(a, qf[st], s);
;                 }
;                 if (kbase + 31 > qw0) {
;                     int dbase = qpos - kbase - 4 * hi;
;                     asm volatile("" : "+v"(dbase));
; #pragma unroll
;                     for (int i = 0; i < 16; ++i) if ((dbase - ((i & 3) + 8 * (i >> 2))) < 0) s[i] = -1e30f;
;                 }
;                 float mx = max16(s);
;                 mx = xhalf_max(mx);
;                 const float mn = (mx > m + 8.f) ? mx : m, alpha = fexp2(m - mn); m = mn; l *= alpha;
;                 if (__any(alpha != 1.f)) {
.LBB0_627:
	s_bitcmp1_b32 s2, 0
	s_cselect_b32 s2, 0xa800, 0
	s_add_i32 s46, s2, 0
	v_add3_u32 v168, v148, v178, s46
	v_add3_u32 v181, v153, v177, s46
	v_add_u32_e32 v230, 0x6000, v181
	v_add_u32_e32 v231, 0x7000, v181
	v_add_u32_e32 v232, 0x8000, v181
	v_add_u32_e32 v233, 0x9000, v181
	ds_read_b128 v[182:185], v168
	ds_read_b128 v[186:189], v168 offset:32
	ds_read_b128 v[190:193], v168 offset:64
	ds_read_b128 v[194:197], v168 offset:96
	ds_read_b128 v[198:201], v168 offset:128
	ds_read_b128 v[202:205], v168 offset:160
	s_waitcnt lgkmcnt(5)
	v_mfma_f32_32x32x16_bf16 v[64:79], v[182:185], v[80:83], v[240:255]
	ds_read_b128 v[182:185], v168 offset:192
	s_waitcnt lgkmcnt(5)
	v_mfma_f32_32x32x16_bf16 v[64:79], v[186:189], v[84:87], v[64:79]
	ds_read_b128 v[186:189], v168 offset:224
	s_waitcnt lgkmcnt(5)
	v_mfma_f32_32x32x16_bf16 v[64:79], v[190:193], v[88:91], v[64:79]
	ds_read_b128 v[190:193], v168 offset:256
	s_waitcnt lgkmcnt(5)
	v_mfma_f32_32x32x16_bf16 v[64:79], v[194:197], v[92:95], v[64:79]
	ds_read_b128 v[194:197], v168 offset:288
	s_waitcnt lgkmcnt(5)
	v_mfma_f32_32x32x16_bf16 v[64:79], v[198:201], v[96:99], v[64:79]
	ds_read_b128 v[198:201], v168 offset:320
	s_waitcnt lgkmcnt(5)
	v_mfma_f32_32x32x16_bf16 v[64:79], v[202:205], v[100:103], v[64:79]
	ds_read_b128 v[202:205], v168 offset:352
	s_waitcnt lgkmcnt(5)
	v_mfma_f32_32x32x16_bf16 v[64:79], v[182:185], v[104:107], v[64:79]
	ds_read2_b64 v[206:209], v230 offset0:128 offset1:130
	s_waitcnt lgkmcnt(5)
	v_mfma_f32_32x32x16_bf16 v[64:79], v[186:189], v[108:111], v[64:79]
	ds_read2_b64 v[210:213], v230 offset0:132 offset1:134
	s_waitcnt lgkmcnt(5)
	v_mfma_f32_32x32x16_bf16 v[64:79], v[190:193], v[112:115], v[64:79]
	ds_read2_b64 v[214:217], v231 offset0:164 offset1:166
	s_waitcnt lgkmcnt(5)
	v_mfma_f32_32x32x16_bf16 v[64:79], v[194:197], v[116:119], v[64:79]
	ds_read2_b64 v[218:221], v231 offset0:160 offset1:162
	s_waitcnt lgkmcnt(5)
	v_mfma_f32_32x32x16_bf16 v[64:79], v[198:201], v[120:123], v[64:79]
	ds_read2_b64 v[222:225], v232 offset0:192 offset1:194
	s_waitcnt lgkmcnt(5)
	v_mfma_f32_32x32x16_bf16 v[64:79], v[202:205], v[124:127], v[64:79]
	ds_read2_b64 v[226:229], v232 offset0:196 offset1:198
	s_add_i32 s2, s80, 31
	s_cmp_le_i32 s2, s58
	s_nop 7
	s_cbranch_scc1 .Lmla_nomask_0
	v_mov_b32_e32 v236, v179
	s_nop 0
	v_cmp_gt_i32_e64 s[30:31], 26, v236
	v_cmp_gt_i32_e64 s[34:35], 27, v236
	v_cmp_gt_i32_e64 s[28:29], 25, v236
	s_and_b64 s[30:31], s[34:35], s[30:31]
	v_cmp_gt_i32_e64 s[26:27], 24, v236
	s_and_b64 s[28:29], s[30:31], s[28:29]
	v_cmp_gt_i32_e64 s[24:25], 19, v236
	s_and_b64 s[26:27], s[28:29], s[26:27]
	v_cmp_gt_i32_e64 s[22:23], 18, v236
	s_and_b64 s[24:25], s[26:27], s[24:25]
	v_cmp_gt_i32_e64 s[20:21], 17, v236
	s_and_b64 s[22:23], s[24:25], s[22:23]
	v_cmp_gt_i32_e64 s[18:19], 16, v236
	s_and_b64 s[20:21], s[22:23], s[20:21]
	v_cmp_gt_i32_e64 s[16:17], 11, v236
	s_and_b64 s[18:19], s[20:21], s[18:19]
	v_cmp_gt_i32_e64 s[14:15], 10, v236
	s_and_b64 s[16:17], s[18:19], s[16:17]
	v_cmp_gt_i32_e64 s[10:11], 9, v236
	s_and_b64 s[14:15], s[16:17], s[14:15]
	v_cmp_gt_i32_e64 s[8:9], 8, v236
	s_and_b64 s[10:11], s[14:15], s[10:11]
	v_cmp_gt_i32_e64 s[6:7], 3, v236
	s_and_b64 s[8:9], s[10:11], s[8:9]
	v_cmp_gt_i32_e64 s[4:5], 2, v236
	s_and_b64 s[6:7], s[8:9], s[6:7]
	v_cmp_gt_i32_e64 s[2:3], 1, v236
	s_and_b64 s[4:5], s[6:7], s[4:5]
	v_cmp_gt_i32_e32 vcc, 0, v236
	s_and_b64 s[2:3], s[4:5], s[2:3]
	s_and_b64 vcc, s[2:3], vcc
	s_nop 1
	v_cndmask_b32_e64 v79, v79, v170, s[34:35]
	v_cndmask_b32_e64 v78, v78, v170, s[30:31]
	v_cndmask_b32_e64 v77, v77, v170, s[28:29]
	v_cndmask_b32_e64 v76, v76, v170, s[26:27]
	v_cndmask_b32_e64 v75, v75, v170, s[24:25]
	v_cndmask_b32_e64 v74, v74, v170, s[22:23]
	v_cndmask_b32_e64 v73, v73, v170, s[20:21]
	v_cndmask_b32_e64 v72, v72, v170, s[18:19]
	v_cndmask_b32_e64 v71, v71, v170, s[16:17]
	v_cndmask_b32_e64 v70, v70, v170, s[14:15]
	v_cndmask_b32_e64 v69, v69, v170, s[10:11]
	v_cndmask_b32_e64 v68, v68, v170, s[8:9]
	v_cndmask_b32_e64 v67, v67, v170, s[6:7]
	v_cndmask_b32_e64 v66, v66, v170, s[4:5]
	v_cndmask_b32_e64 v65, v65, v170, s[2:3]
	v_cndmask_b32_e32 v64, v64, v170, vcc
.Lmla_nomask_0:
	v_max3_f32 v236, v64, v65, v66
	v_max3_f32 v237, v67, v68, v69
	v_max3_f32 v238, v70, v71, v72
	v_max3_f32 v239, v73, v74, v75
	v_max3_f32 v236, v236, v76, v77
	v_max3_f32 v237, v237, v78, v79
	v_max3_f32 v236, v236, v237, v238
	v_max3_f32 v236, v236, v239, v239
	v_mov_b32_e32 v237, v236
	s_nop 1
	v_permlane32_swap_b32_e32 v236, v237
	s_nop 0
	v_max_f32_e32 v236, v236, v237
	v_sub_f32_e32 v236, v236, v240
	v_add_f32_e32 v237, 0x41000000, v180
	v_cmp_gt_f32_e32 vcc, v236, v237
	s_nop 1
	v_cndmask_b32_e32 v237, v180, v236, vcc
	v_sub_f32_e32 v166, v180, v237
	v_mov_b32_e32 v180, v237
	v_exp_f32_e32 v166, v166
	s_nop 0
	v_cmp_neq_f32_e32 vcc, 1.0, v166
	s_cbranch_vccz .Lmla_norescale_0
; DI void mla_unit(const Params& p, LAS unsigned char* lds, int b, int h, int qb, int tid) {
;     ...
;                 if (__any(alpha != 1.f)) {
; #pragma unroll
;                     for (int db = 0; db < 4; ++db) o[db] = o[db] * alpha;
;                 }
	v_pk_mul_f32 v[62:63], v[62:63], v[166:167] op_sel_hi:[1,0]
	v_pk_mul_f32 v[60:61], v[60:61], v[166:167] op_sel_hi:[1,0]
	v_pk_mul_f32 v[58:59], v[58:59], v[166:167] op_sel_hi:[1,0]
	v_pk_mul_f32 v[56:57], v[56:57], v[166:167] op_sel_hi:[1,0]
	v_pk_mul_f32 v[54:55], v[54:55], v[166:167] op_sel_hi:[1,0]
	v_pk_mul_f32 v[52:53], v[52:53], v[166:167] op_sel_hi:[1,0]
	v_pk_mul_f32 v[50:51], v[50:51], v[166:167] op_sel_hi:[1,0]
	v_pk_mul_f32 v[48:49], v[48:49], v[166:167] op_sel_hi:[1,0]
	v_pk_mul_f32 v[46:47], v[46:47], v[166:167] op_sel_hi:[1,0]
	v_pk_mul_f32 v[44:45], v[44:45], v[166:167] op_sel_hi:[1,0]
	v_pk_mul_f32 v[42:43], v[42:43], v[166:167] op_sel_hi:[1,0]
	v_pk_mul_f32 v[40:41], v[40:41], v[166:167] op_sel_hi:[1,0]
	v_pk_mul_f32 v[38:39], v[38:39], v[166:167] op_sel_hi:[1,0]
	v_pk_mul_f32 v[36:37], v[36:37], v[166:167] op_sel_hi:[1,0]
	v_pk_mul_f32 v[34:35], v[34:35], v[166:167] op_sel_hi:[1,0]
	v_pk_mul_f32 v[32:33], v[32:33], v[166:167] op_sel_hi:[1,0]
	v_pk_mul_f32 v[30:31], v[30:31], v[166:167] op_sel_hi:[1,0]
	v_pk_mul_f32 v[28:29], v[28:29], v[166:167] op_sel_hi:[1,0]
	v_pk_mul_f32 v[26:27], v[26:27], v[166:167] op_sel_hi:[1,0]
	v_pk_mul_f32 v[24:25], v[24:25], v[166:167] op_sel_hi:[1,0]
	v_pk_mul_f32 v[22:23], v[22:23], v[166:167] op_sel_hi:[1,0]
	v_pk_mul_f32 v[20:21], v[20:21], v[166:167] op_sel_hi:[1,0]
	v_pk_mul_f32 v[18:19], v[18:19], v[166:167] op_sel_hi:[1,0]
	v_pk_mul_f32 v[16:17], v[16:17], v[166:167] op_sel_hi:[1,0]
	v_pk_mul_f32 v[14:15], v[14:15], v[166:167] op_sel_hi:[1,0]
	v_pk_mul_f32 v[12:13], v[12:13], v[166:167] op_sel_hi:[1,0]
	v_pk_mul_f32 v[10:11], v[10:11], v[166:167] op_sel_hi:[1,0]
	v_pk_mul_f32 v[8:9], v[8:9], v[166:167] op_sel_hi:[1,0]
	v_pk_mul_f32 v[6:7], v[6:7], v[166:167] op_sel_hi:[1,0]
	v_pk_mul_f32 v[4:5], v[4:5], v[166:167] op_sel_hi:[1,0]
	v_pk_mul_f32 v[2:3], v[2:3], v[166:167] op_sel_hi:[1,0]
	v_pk_mul_f32 v[0:1], v[0:1], v[166:167] op_sel_hi:[1,0]
	v_cmp_lt_f32_e32 vcc, 0xdf0ac723, v180
	s_nop 1
	v_cndmask_b32_e32 v238, 0, v180, vcc
	v_add_f32_e32 v239, v238, v240
	v_sub_f32_e32 v240, v240, v239
	v_sub_f32_e32 v241, v241, v239
	v_sub_f32_e32 v242, v242, v239
	v_sub_f32_e32 v243, v243, v239
	v_sub_f32_e32 v244, v244, v239
	v_sub_f32_e32 v245, v245, v239
	v_sub_f32_e32 v246, v246, v239
	v_sub_f32_e32 v247, v247, v239
	v_sub_f32_e32 v248, v248, v239
	v_sub_f32_e32 v249, v249, v239
	v_sub_f32_e32 v250, v250, v239
	v_sub_f32_e32 v251, v251, v239
	v_sub_f32_e32 v252, v252, v239
	v_sub_f32_e32 v253, v253, v239
	v_sub_f32_e32 v254, v254, v239
	v_sub_f32_e32 v255, v255, v239
	v_sub_f32_e32 v64, v64, v239
	v_sub_f32_e32 v65, v65, v239
	v_sub_f32_e32 v66, v66, v239
	v_sub_f32_e32 v67, v67, v239
	v_sub_f32_e32 v68, v68, v239
	v_sub_f32_e32 v69, v69, v239
	v_sub_f32_e32 v70, v70, v239
	v_sub_f32_e32 v71, v71, v239
	v_sub_f32_e32 v72, v72, v239
	v_sub_f32_e32 v73, v73, v239
	v_sub_f32_e32 v74, v74, v239
	v_sub_f32_e32 v75, v75, v239
	v_sub_f32_e32 v76, v76, v239
	v_sub_f32_e32 v77, v77, v239
	v_sub_f32_e32 v78, v78, v239
	v_sub_f32_e32 v79, v79, v239
; #define LAS __attribute__((address_space(3)))
; DI float fexp2(float x) { return __builtin_amdgcn_exp2f(x); }
; #define MFMA32(a, b, c) __builtin_amdgcn_mfma_f32_32x32x16_bf16((a), (b), (c), 0, 0, 0)
; DI void mla_unit(const Params& p, LAS unsigned char* lds, int b, int h, int qb, int tid) {
;     ...
;             for (int sub = 0; sub < 2; ++sub) {
;                 const int kbase = kt * 64 + 32 * sub;
;                 f32x16 s;
; #pragma unroll
;                 for (int i = 0; i < 16; ++i) s[i] = 0.f;
; #pragma unroll
;                 for (int st = 0; st < 12; ++st) {
;                     const bf16x8 a = *(LAS const bf16x8*)(buf + (32 * sub + c) * 400 + st * 32 + hi * 16);
;                     s = MFMA32(a, qf[st], s);
;                 }
;                 if (kbase + 31 > qw0) {
;                     int dbase = qpos - kbase - 4 * hi;
;                     asm volatile("" : "+v"(dbase));
; #pragma unroll
;                     for (int i = 0; i < 16; ++i) if ((dbase - ((i & 3) + 8 * (i >> 2))) < 0) s[i] = -1e30f;
;     ...
;                 float ps = 0.f;
; #pragma unroll
;                 for (int i = 0; i < 16; ++i) { const float pv = fexp2(s[i] - m); s[i] = pv; ps += pv; }
;                 l += ps;
;                 const bf16x8 pb0 = packp(s, 0), pb1 = packp(s, 1);
; #pragma unroll
;                 for (int db = 0; db < 4; ++db) {
;                     LAS const unsigned char* ap = buf + 25600 + (32 * db + c) * 136 + (32 * sub + 4 * hi) * 2;
;                     const bf16x8 v0 = cat4(*(LAS const bf16x4*)(ap), *(LAS const bf16x4*)(ap + 16));
;                     const bf16x8 v1 = cat4(*(LAS const bf16x4*)(ap + 32), *(LAS const bf16x4*)(ap + 48));
;                     o[db] = MFMA32(v0, pb0, o[db]); o[db] = MFMA32(v1, pb1, o[db]);
.Lmla_norescale_0:
	v_exp_f32_e32 v64, v64
	v_exp_f32_e32 v65, v65
	v_exp_f32_e32 v66, v66
	v_exp_f32_e32 v67, v67
	v_exp_f32_e32 v68, v68
	v_exp_f32_e32 v69, v69
	v_exp_f32_e32 v70, v70
	v_exp_f32_e32 v71, v71
	v_exp_f32_e32 v72, v72
	v_exp_f32_e32 v73, v73
	v_exp_f32_e32 v74, v74
	v_exp_f32_e32 v75, v75
	v_exp_f32_e32 v76, v76
	v_exp_f32_e32 v77, v77
	v_exp_f32_e32 v78, v78
	v_exp_f32_e32 v79, v79
	v_add_f32_e32 v236, v64, v65
	v_add_f32_e32 v237, v66, v67
	v_cvt_pk_bf16_f32 v198, v64, v65
	v_cvt_pk_bf16_f32 v199, v66, v67
	v_cvt_pk_bf16_f32 v200, v68, v69
	v_cvt_pk_bf16_f32 v201, v70, v71
	v_cvt_pk_bf16_f32 v202, v72, v73
	v_cvt_pk_bf16_f32 v203, v74, v75
	v_cvt_pk_bf16_f32 v204, v76, v77
	v_cvt_pk_bf16_f32 v205, v78, v79
	v_add_f32_e32 v238, v68, v69
	v_add_f32_e32 v239, v70, v71
	s_waitcnt lgkmcnt(5)
	v_mfma_f32_32x32x16_bf16 v[48:63], v[206:209], v[198:201], v[48:63]
	ds_read2_b64 v[206:209], v233 offset0:228 offset1:230
	v_add_f32_e32 v236, v236, v72
	v_add_f32_e32 v237, v237, v73
	s_waitcnt lgkmcnt(5)
	v_mfma_f32_32x32x16_bf16 v[48:63], v[210:213], v[202:205], v[48:63]
	ds_read2_b64 v[210:213], v233 offset0:224 offset1:226
	v_add_f32_e32 v238, v238, v74
	v_add_f32_e32 v239, v239, v75
	s_waitcnt lgkmcnt(5)
	v_mfma_f32_32x32x16_bf16 v[32:47], v[214:217], v[202:205], v[32:47]
	ds_read_b128 v[182:185], v168 offset:12800
	v_add_f32_e32 v236, v236, v76
	v_add_f32_e32 v237, v237, v77
	s_waitcnt lgkmcnt(5)
	v_mfma_f32_32x32x16_bf16 v[32:47], v[218:221], v[198:201], v[32:47]
	ds_read_b128 v[186:189], v168 offset:12832
	v_add_f32_e32 v238, v238, v78
	v_add_f32_e32 v239, v239, v79
	s_waitcnt lgkmcnt(5)
	v_mfma_f32_32x32x16_bf16 v[16:31], v[222:225], v[198:201], v[16:31]
	ds_read_b128 v[190:193], v168 offset:12864
	v_add_f32_e32 v236, v236, v237
	s_waitcnt lgkmcnt(5)
	v_mfma_f32_32x32x16_bf16 v[16:31], v[226:229], v[202:205], v[16:31]
	ds_read_b128 v[194:197], v168 offset:12896
	v_add_f32_e32 v238, v238, v239
	s_waitcnt lgkmcnt(5)
	v_mfma_f32_32x32x16_bf16 v[0:15], v[206:209], v[202:205], v[0:15]
	v_add_f32_e32 v236, v236, v238
	s_waitcnt lgkmcnt(4)
	v_mfma_f32_32x32x16_bf16 v[0:15], v[210:213], v[198:201], v[0:15]
	v_fma_f32 v155, v155, v166, v236
	ds_read_b128 v[198:201], v168 offset:12928
	ds_read_b128 v[202:205], v168 offset:12960
	s_waitcnt lgkmcnt(5)
	v_mfma_f32_32x32x16_bf16 v[64:79], v[182:185], v[80:83], v[240:255]
	ds_read_b128 v[182:185], v168 offset:12992
	s_waitcnt lgkmcnt(5)
	v_mfma_f32_32x32x16_bf16 v[64:79], v[186:189], v[84:87], v[64:79]
	ds_read_b128 v[186:189], v168 offset:13024
	s_waitcnt lgkmcnt(5)
	v_mfma_f32_32x32x16_bf16 v[64:79], v[190:193], v[88:91], v[64:79]
	ds_read_b128 v[190:193], v168 offset:13056
	s_waitcnt lgkmcnt(5)
	v_mfma_f32_32x32x16_bf16 v[64:79], v[194:197], v[92:95], v[64:79]
	ds_read_b128 v[194:197], v168 offset:13088
	s_waitcnt lgkmcnt(5)
	v_mfma_f32_32x32x16_bf16 v[64:79], v[198:201], v[96:99], v[64:79]
	ds_read_b128 v[198:201], v168 offset:13120
	s_waitcnt lgkmcnt(5)
	v_mfma_f32_32x32x16_bf16 v[64:79], v[202:205], v[100:103], v[64:79]
	ds_read_b128 v[202:205], v168 offset:13152
	s_waitcnt lgkmcnt(5)
	v_mfma_f32_32x32x16_bf16 v[64:79], v[182:185], v[104:107], v[64:79]
	ds_read2_b64 v[206:209], v230 offset0:136 offset1:138
	s_waitcnt lgkmcnt(5)
	v_mfma_f32_32x32x16_bf16 v[64:79], v[186:189], v[108:111], v[64:79]
	ds_read2_b64 v[210:213], v230 offset0:140 offset1:142
	s_waitcnt lgkmcnt(5)
	v_mfma_f32_32x32x16_bf16 v[64:79], v[190:193], v[112:115], v[64:79]
	ds_read2_b64 v[214:217], v231 offset0:172 offset1:174
	s_waitcnt lgkmcnt(5)
	v_mfma_f32_32x32x16_bf16 v[64:79], v[194:197], v[116:119], v[64:79]
	ds_read2_b64 v[218:221], v231 offset0:168 offset1:170
	s_waitcnt lgkmcnt(5)
	v_mfma_f32_32x32x16_bf16 v[64:79], v[198:201], v[120:123], v[64:79]
	ds_read2_b64 v[222:225], v232 offset0:200 offset1:202
	s_waitcnt lgkmcnt(5)
	v_mfma_f32_32x32x16_bf16 v[64:79], v[202:205], v[124:127], v[64:79]
	ds_read2_b64 v[226:229], v232 offset0:204 offset1:206
	s_add_i32 s2, s80, 63
	s_cmp_le_i32 s2, s58
	s_nop 7
	s_cbranch_scc1 .Lmla_nomask_1
	v_subrev_u32_e32 v236, 32, v179
	s_nop 0
	v_cmp_gt_i32_e64 s[30:31], 26, v236
	v_cmp_gt_i32_e64 s[34:35], 27, v236
	v_cmp_gt_i32_e64 s[28:29], 25, v236
	s_and_b64 s[30:31], s[34:35], s[30:31]
	v_cmp_gt_i32_e64 s[26:27], 24, v236
	s_and_b64 s[28:29], s[30:31], s[28:29]
	v_cmp_gt_i32_e64 s[24:25], 19, v236
	s_and_b64 s[26:27], s[28:29], s[26:27]
	v_cmp_gt_i32_e64 s[22:23], 18, v236
	s_and_b64 s[24:25], s[26:27], s[24:25]
	v_cmp_gt_i32_e64 s[20:21], 17, v236
	s_and_b64 s[22:23], s[24:25], s[22:23]
	v_cmp_gt_i32_e64 s[18:19], 16, v236
	s_and_b64 s[20:21], s[22:23], s[20:21]
	v_cmp_gt_i32_e64 s[16:17], 11, v236
	s_and_b64 s[18:19], s[20:21], s[18:19]
	v_cmp_gt_i32_e64 s[14:15], 10, v236
	s_and_b64 s[16:17], s[18:19], s[16:17]
	v_cmp_gt_i32_e64 s[10:11], 9, v236
	s_and_b64 s[14:15], s[16:17], s[14:15]
	v_cmp_gt_i32_e64 s[8:9], 8, v236
	s_and_b64 s[10:11], s[14:15], s[10:11]
	v_cmp_gt_i32_e64 s[6:7], 3, v236
	s_and_b64 s[8:9], s[10:11], s[8:9]
	v_cmp_gt_i32_e64 s[4:5], 2, v236
	s_and_b64 s[6:7], s[8:9], s[6:7]
	v_cmp_gt_i32_e64 s[2:3], 1, v236
	s_and_b64 s[4:5], s[6:7], s[4:5]
	v_cmp_gt_i32_e32 vcc, 0, v236
	s_and_b64 s[2:3], s[4:5], s[2:3]
	s_and_b64 vcc, s[2:3], vcc
	s_nop 1
	v_cndmask_b32_e64 v79, v79, v170, s[34:35]
	v_cndmask_b32_e64 v78, v78, v170, s[30:31]
	v_cndmask_b32_e64 v77, v77, v170, s[28:29]
	v_cndmask_b32_e64 v76, v76, v170, s[26:27]
	v_cndmask_b32_e64 v75, v75, v170, s[24:25]
	v_cndmask_b32_e64 v74, v74, v170, s[22:23]
	v_cndmask_b32_e64 v73, v73, v170, s[20:21]
	v_cndmask_b32_e64 v72, v72, v170, s[18:19]
	v_cndmask_b32_e64 v71, v71, v170, s[16:17]
	v_cndmask_b32_e64 v70, v70, v170, s[14:15]
	v_cndmask_b32_e64 v69, v69, v170, s[10:11]
	v_cndmask_b32_e64 v68, v68, v170, s[8:9]
	v_cndmask_b32_e64 v67, v67, v170, s[6:7]
	v_cndmask_b32_e64 v66, v66, v170, s[4:5]
	v_cndmask_b32_e64 v65, v65, v170, s[2:3]
	v_cndmask_b32_e32 v64, v64, v170, vcc

; #define LAS __attribute__((address_space(3)))
; DI float fexp2(float x) { return __builtin_amdgcn_exp2f(x); }
; #define MFMA32(a, b, c) __builtin_amdgcn_mfma_f32_32x32x16_bf16((a), (b), (c), 0, 0, 0)
; DI void mla_unit(const Params& p, LAS unsigned char* lds, int b, int h, int qb, int tid) {
;     ...
;                 float ps = 0.f;
; #pragma unroll
;                 for (int i = 0; i < 16; ++i) { const float pv = fexp2(s[i] - m); s[i] = pv; ps += pv; }
;                 l += ps;
;                 const bf16x8 pb0 = packp(s, 0), pb1 = packp(s, 1);
; #pragma unroll
;                 for (int db = 0; db < 4; ++db) {
;                     LAS const unsigned char* ap = buf + 25600 + (32 * db + c) * 136 + (32 * sub + 4 * hi) * 2;
;                     const bf16x8 v0 = cat4(*(LAS const bf16x4*)(ap), *(LAS const bf16x4*)(ap + 16));
;                     const bf16x8 v1 = cat4(*(LAS const bf16x4*)(ap + 32), *(LAS const bf16x4*)(ap + 48));
;                     o[db] = MFMA32(v0, pb0, o[db]); o[db] = MFMA32(v1, pb1, o[db]);
;                 }
.Lmla_norescale_1:
	v_exp_f32_e32 v64, v64
	v_exp_f32_e32 v65, v65
	v_exp_f32_e32 v66, v66
	v_exp_f32_e32 v67, v67
	v_exp_f32_e32 v68, v68
	v_exp_f32_e32 v69, v69
	v_exp_f32_e32 v70, v70
	v_exp_f32_e32 v71, v71
	v_exp_f32_e32 v72, v72
	v_exp_f32_e32 v73, v73
	v_exp_f32_e32 v74, v74
	v_exp_f32_e32 v75, v75
	v_exp_f32_e32 v76, v76
	v_exp_f32_e32 v77, v77
	v_exp_f32_e32 v78, v78
	v_exp_f32_e32 v79, v79
	v_add_f32_e32 v236, v64, v65
	v_add_f32_e32 v237, v66, v67
	v_cvt_pk_bf16_f32 v198, v64, v65
	v_cvt_pk_bf16_f32 v199, v66, v67
	v_cvt_pk_bf16_f32 v200, v68, v69
	v_cvt_pk_bf16_f32 v201, v70, v71
	v_cvt_pk_bf16_f32 v202, v72, v73
	v_cvt_pk_bf16_f32 v203, v74, v75
	v_cvt_pk_bf16_f32 v204, v76, v77
	v_cvt_pk_bf16_f32 v205, v78, v79
	v_add_f32_e32 v238, v68, v69
	v_add_f32_e32 v239, v70, v71
	s_waitcnt lgkmcnt(5)
	v_mfma_f32_32x32x16_bf16 v[48:63], v[206:209], v[198:201], v[48:63]
	ds_read2_b64 v[206:209], v233 offset0:236 offset1:238
	v_add_f32_e32 v236, v236, v72
	v_add_f32_e32 v237, v237, v73
	s_waitcnt lgkmcnt(5)
	v_mfma_f32_32x32x16_bf16 v[48:63], v[210:213], v[202:205], v[48:63]
	ds_read2_b64 v[210:213], v233 offset0:232 offset1:234
	v_add_f32_e32 v238, v238, v74
	v_add_f32_e32 v239, v239, v75
	s_waitcnt lgkmcnt(5)
	v_mfma_f32_32x32x16_bf16 v[32:47], v[214:217], v[202:205], v[32:47]
	v_add_f32_e32 v236, v236, v76
	v_add_f32_e32 v237, v237, v77
	s_waitcnt lgkmcnt(4)
	v_mfma_f32_32x32x16_bf16 v[32:47], v[218:221], v[198:201], v[32:47]
	v_add_f32_e32 v238, v238, v78
	v_add_f32_e32 v239, v239, v79
	s_waitcnt lgkmcnt(3)
	v_mfma_f32_32x32x16_bf16 v[16:31], v[222:225], v[198:201], v[16:31]
	v_add_f32_e32 v236, v236, v237
	s_waitcnt lgkmcnt(2)
	v_mfma_f32_32x32x16_bf16 v[16:31], v[226:229], v[202:205], v[16:31]
	v_add_f32_e32 v238, v238, v239
	s_waitcnt lgkmcnt(1)
	v_mfma_f32_32x32x16_bf16 v[0:15], v[206:209], v[202:205], v[0:15]
	v_add_f32_e32 v236, v236, v238
	s_waitcnt lgkmcnt(0)
	v_mfma_f32_32x32x16_bf16 v[0:15], v[210:213], v[198:201], v[0:15]
	v_fma_f32 v155, v155, v166, v236
	s_andn2_b64 vcc, exec, s[76:77]
	s_cbranch_vccz .LBB0_623
	s_branch .LBB0_624

; DI float fexp2(float x) { return __builtin_amdgcn_exp2f(x); }
; DI void nsa_unit(const Params& p, LAS unsigned char* lds, unsigned char* ldsg, int bg, int qt, int tid) {
;     ...
;             const float mn = fmaxf(m1, max16(s));
;             float ps = 0.f;
; #pragma unroll
;             for (int i = 0; i < 16; ++i) ps += fexp2(s[i] - mn);
;             l1 = l1 * fexp2(m1 - mn) + ps; m1 = mn;
.LBB0_726:
	v_max3_f32 v25, v2, v3, v4
	v_max3_f32 v26, v5, v6, v7
	v_max3_f32 v27, v8, v9, v10
	v_max3_f32 v28, v11, v12, v13
	s_add_i32 s46, s46, -1
	v_max3_f32 v25, v25, v14, v15
	v_max3_f32 v26, v26, v16, v17
	s_addk_i32 s39, 0x200
	v_max3_f32 v25, v25, v26, v27
	v_max_f32_e32 v26, v24, v24
	v_max3_f32 v25, v25, v28, v28
	v_add_u32_e32 v21, 0x1200, v21
	v_max_f32_e32 v25, v25, v25
	v_max_f32_e32 v25, v26, v25
	s_nop 4
	v_sub_f32_e32 v2, v2, v25
	v_exp_f32_e32 v2, v2
	v_sub_f32_e32 v3, v3, v25
	v_exp_f32_e32 v3, v3
	v_sub_f32_e32 v4, v4, v25
	v_exp_f32_e32 v4, v4
	v_sub_f32_e32 v5, v5, v25
	v_exp_f32_e32 v5, v5
	v_sub_f32_e32 v6, v6, v25
	v_exp_f32_e32 v6, v6
	v_add_f32_e32 v2, v3, v2
	v_sub_f32_e32 v3, v7, v25
	v_add_f32_e32 v2, v4, v2
	v_exp_f32_e32 v3, v3
	v_sub_f32_e32 v4, v8, v25
	v_add_f32_e32 v2, v5, v2
	v_exp_f32_e32 v4, v4
	v_sub_f32_e32 v5, v9, v25
	v_add_f32_e32 v2, v6, v2
	v_exp_f32_e32 v5, v5
	v_sub_f32_e32 v6, v10, v25
	v_exp_f32_e32 v6, v6
	v_add_f32_e32 v2, v3, v2
	v_sub_f32_e32 v3, v11, v25
	v_add_f32_e32 v2, v4, v2
	v_exp_f32_e32 v3, v3
	v_sub_f32_e32 v4, v12, v25
	v_add_f32_e32 v2, v5, v2
	v_exp_f32_e32 v4, v4
	v_sub_f32_e32 v5, v13, v25
	v_add_f32_e32 v2, v6, v2
	v_exp_f32_e32 v5, v5
	v_sub_f32_e32 v6, v14, v25
	v_exp_f32_e32 v6, v6
	v_add_f32_e32 v2, v3, v2
	v_sub_f32_e32 v3, v15, v25
	v_add_f32_e32 v2, v4, v2
	v_exp_f32_e32 v3, v3
	v_sub_f32_e32 v4, v16, v25
	v_add_f32_e32 v2, v5, v2
	v_exp_f32_e32 v4, v4
	v_sub_f32_e32 v5, v17, v25
	v_add_f32_e32 v2, v6, v2
	v_exp_f32_e32 v5, v5
	v_sub_f32_e32 v6, v24, v25
	v_exp_f32_e32 v6, v6
	v_add_f32_e32 v2, v3, v2
	v_add_f32_e32 v2, v4, v2
	v_add_f32_e32 v2, v5, v2
	v_fmac_f32_e32 v2, v23, v6
	s_cmp_eq_u32 s46, 0
	v_add_u32_e32 v22, 0xfffffe00, v22
	s_cbranch_scc1 .LBB0_729
	v_mov_b32_e32 v24, v25
	v_mov_b32_e32 v23, v2
	s_branch .LBB0_724

; DI float xhalf_max(float v) { unsigned a = __builtin_bit_cast(unsigned, v), b = a; swap32(a, b); return fmaxf(__builtin_bit_cast(float, a), __builtin_bit_cast(float, b)); }
; DI float fexp2(float x) { return __builtin_amdgcn_exp2f(x); }
; template <int MODE>
; DI void nsa_tile(LAS const unsigned char* buf, const bf16x8 (&qf)[4], f32x16 (&o)[2], float& m, float& l, int kbase0, int t, bool lanesel, float slope2, int c, int hi) {
;     ...
;         float mx = max16(s);
;         mx = xhalf_max(mx);
;         if (__any(mx > m + 8.f)) {
;             const float mn = fmaxf(m, mx), alpha = fexp2(m - mn); m = mn; l *= alpha;
;             o[0] = o[0] * alpha; o[1] = o[1] * alpha;
;         }
;         float ps = 0.f;
; #pragma unroll
;         for (int i = 0; i < 16; ++i) { const float pv = fexp2(s[i] - m); s[i] = pv; ps += pv; }
;         l += ps;
.LBB0_826:
	v_max3_f32 v120, v80, v81, v82
	v_max3_f32 v121, v83, v84, v85
	v_max3_f32 v122, v86, v87, v88
	v_max3_f32 v123, v89, v90, v91
	s_nop 0
	v_max3_f32 v120, v120, v92, v93
	v_max3_f32 v121, v121, v94, v95
	s_nop 0
	v_max3_f32 v120, v120, v121, v122
	s_nop 0
	v_max3_f32 v120, v120, v123, v123
	s_nop 0
	v_mov_b32_e32 v121, v120
	s_nop 1
	v_permlane32_swap_b32 v120, v121
	s_nop 0
	v_max_f32_e32 v120, v120, v121
	v_add_f32_e32 v120, v120, v248
	v_add_f32_e32 v121, 0x41000000, v118
	v_cmp_gt_f32_e32 vcc, v120, v121
	s_cbranch_vccz .LBB0_828
	v_max_f32_e32 v120, v120, v120
	v_max_f32_e32 v121, v118, v118
	v_max_f32_e32 v120, v121, v120
	v_sub_f32_e32 v118, v118, v120
	v_exp_f32_e32 v118, v118
	s_nop 0
	v_mul_f32_e32 v175, v175, v118
	v_pk_mul_f32 v[78:79], v[78:79], v[118:119] op_sel_hi:[1,0]
	v_pk_mul_f32 v[76:77], v[76:77], v[118:119] op_sel_hi:[1,0]
	v_pk_mul_f32 v[74:75], v[74:75], v[118:119] op_sel_hi:[1,0]
	v_pk_mul_f32 v[72:73], v[72:73], v[118:119] op_sel_hi:[1,0]
	v_pk_mul_f32 v[70:71], v[70:71], v[118:119] op_sel_hi:[1,0]
	v_pk_mul_f32 v[68:69], v[68:69], v[118:119] op_sel_hi:[1,0]
	v_pk_mul_f32 v[66:67], v[66:67], v[118:119] op_sel_hi:[1,0]
	v_pk_mul_f32 v[64:65], v[64:65], v[118:119] op_sel_hi:[1,0]
	v_pk_mul_f32 v[62:63], v[62:63], v[118:119] op_sel_hi:[1,0]
	v_pk_mul_f32 v[60:61], v[60:61], v[118:119] op_sel_hi:[1,0]
	v_pk_mul_f32 v[58:59], v[58:59], v[118:119] op_sel_hi:[1,0]
	v_pk_mul_f32 v[56:57], v[56:57], v[118:119] op_sel_hi:[1,0]
	v_pk_mul_f32 v[54:55], v[54:55], v[118:119] op_sel_hi:[1,0]
	v_pk_mul_f32 v[52:53], v[52:53], v[118:119] op_sel_hi:[1,0]
	v_pk_mul_f32 v[50:51], v[50:51], v[118:119] op_sel_hi:[1,0]
	v_pk_mul_f32 v[48:49], v[48:49], v[118:119] op_sel_hi:[1,0]
	v_mov_b32_e32 v118, v120
	v_cmp_lt_f32_e32 vcc, 0xdf0ac723, v118
	s_nop 1
	v_cndmask_b32_e32 v250, 0, v118, vcc
	v_sub_f32_e32 v251, v250, v248
	v_mov_b32_e32 v248, v250
	v_sub_f32_e32 v80, v80, v251
	v_sub_f32_e32 v81, v81, v251
	v_sub_f32_e32 v82, v82, v251
	v_sub_f32_e32 v83, v83, v251
	v_sub_f32_e32 v84, v84, v251
	v_sub_f32_e32 v85, v85, v251
	v_sub_f32_e32 v86, v86, v251
	v_sub_f32_e32 v87, v87, v251
	v_sub_f32_e32 v88, v88, v251
	v_sub_f32_e32 v89, v89, v251
	v_sub_f32_e32 v90, v90, v251
	v_sub_f32_e32 v91, v91, v251
	v_sub_f32_e32 v92, v92, v251
	v_sub_f32_e32 v93, v93, v251
	v_sub_f32_e32 v94, v94, v251
	v_sub_f32_e32 v95, v95, v251
.LBB0_828:
	v_exp_f32_e32 v80, v80
	v_exp_f32_e32 v81, v81
	v_exp_f32_e32 v82, v82
	v_exp_f32_e32 v83, v83
	v_exp_f32_e32 v121, v84
	v_add_f32_e32 v120, v81, v80
	v_add_f32_e32 v120, v82, v120
	v_add_f32_e32 v120, v83, v120
	v_add_f32_e32 v84, v121, v120
	v_exp_f32_e32 v120, v85
	v_exp_f32_e32 v122, v86
	v_exp_f32_e32 v87, v87
	v_exp_f32_e32 v88, v88
	v_add_f32_e32 v84, v120, v84
	v_exp_f32_e32 v89, v89
	v_add_f32_e32 v84, v122, v84
	v_exp_f32_e32 v90, v90
	v_add_f32_e32 v84, v87, v84
	v_exp_f32_e32 v91, v91
	v_add_f32_e32 v84, v88, v84
	v_exp_f32_e32 v92, v92
	v_add_f32_e32 v84, v89, v84
	v_exp_f32_e32 v93, v93
	v_add_f32_e32 v84, v90, v84
	v_exp_f32_e32 v94, v94
	v_add_f32_e32 v84, v91, v84
	v_exp_f32_e32 v95, v95
	v_add_f32_e32 v84, v92, v84
	v_add_f32_e32 v84, v93, v84
	v_add_f32_e32 v84, v94, v84
	v_cvt_pk_bf16_f32 v86, v121, v120
	v_add3_u32 v120, s14, v15, v174
	v_add_f32_e32 v84, v95, v84
	v_cvt_pk_bf16_f32 v85, v82, v83
	v_cvt_pk_bf16_f32 v82, v92, v93
	v_add_u32_e32 v92, 0x2000, v120
	v_add_f32_e32 v175, v175, v84
	v_cvt_pk_bf16_f32 v84, v80, v81
	v_cvt_pk_bf16_f32 v80, v88, v89
	v_cvt_pk_bf16_f32 v81, v90, v91
	v_cvt_pk_bf16_f32 v83, v94, v95
	ds_read2_b64 v[88:91], v92 offset0:128 offset1:130
	ds_read2_b64 v[92:95], v92 offset0:132 offset1:134
	v_cvt_pk_bf16_f32 v87, v122, v87
	s_waitcnt lgkmcnt(1)
	s_nop 0
	v_mfma_f32_32x32x16_bf16 v[48:63], v[88:91], v[84:87], v[48:63]
	s_waitcnt lgkmcnt(0)
	v_mfma_f32_32x32x16_bf16 v[48:63], v[92:95], v[80:83], v[48:63]
	v_add_u32_e32 v92, 0x3000, v120
	ds_read2_b64 v[88:91], v92 offset0:160 offset1:162
	s_waitcnt lgkmcnt(0)
	v_mfma_f32_32x32x16_bf16 v[64:79], v[88:91], v[84:87], v[64:79]
	ds_read2_b64 v[84:87], v92 offset0:164 offset1:166
	s_waitcnt lgkmcnt(0)
	v_mfma_f32_32x32x16_bf16 v[64:79], v[84:87], v[80:83], v[64:79]

; DI float xhalf_max(float v) { unsigned a = __builtin_bit_cast(unsigned, v), b = a; swap32(a, b); return fmaxf(__builtin_bit_cast(float, a), __builtin_bit_cast(float, b)); }
; DI float fexp2(float x) { return __builtin_amdgcn_exp2f(x); }
; template <int MODE>
; DI void nsa_tile(LAS const unsigned char* buf, const bf16x8 (&qf)[4], f32x16 (&o)[2], float& m, float& l, int kbase0, int t, bool lanesel, float slope2, int c, int hi) {
;     ...
;         float mx = max16(s);
;         mx = xhalf_max(mx);
;         if (__any(mx > m + 8.f)) {
;             const float mn = fmaxf(m, mx), alpha = fexp2(m - mn); m = mn; l *= alpha;
;             o[0] = o[0] * alpha; o[1] = o[1] * alpha;
;         }
;         float ps = 0.f;
; #pragma unroll
;         for (int i = 0; i < 16; ++i) { const float pv = fexp2(s[i] - m); s[i] = pv; ps += pv; }
;         l += ps;
.LBB0_832:
	v_max3_f32 v119, v80, v81, v82
	v_max3_f32 v120, v83, v84, v85
	v_max3_f32 v121, v86, v87, v88
	v_max3_f32 v122, v89, v90, v91
	s_nop 0
	v_max3_f32 v119, v119, v92, v93
	v_max3_f32 v120, v120, v94, v95
	s_nop 0
	v_max3_f32 v119, v119, v120, v121
	s_nop 0
	v_max3_f32 v119, v119, v122, v122
	s_nop 0
	v_mov_b32_e32 v120, v119
	s_nop 1
	v_permlane32_swap_b32 v119, v120
	s_nop 0
	v_max_f32_e32 v119, v119, v120
	v_add_f32_e32 v119, v119, v248
	v_add_f32_e32 v120, 0x41000000, v118
	v_cmp_gt_f32_e32 vcc, v119, v120
	s_cbranch_vccz .LBB0_834
	v_max_f32_e32 v119, v119, v119
	v_max_f32_e32 v120, v118, v118
	v_max_f32_e32 v119, v120, v119
	v_sub_f32_e32 v118, v118, v119
	v_exp_f32_e32 v118, v118
	s_nop 0
	v_mul_f32_e32 v175, v175, v118
	v_pk_mul_f32 v[78:79], v[78:79], v[118:119] op_sel_hi:[1,0]
	v_pk_mul_f32 v[76:77], v[76:77], v[118:119] op_sel_hi:[1,0]
	v_pk_mul_f32 v[74:75], v[74:75], v[118:119] op_sel_hi:[1,0]
	v_pk_mul_f32 v[72:73], v[72:73], v[118:119] op_sel_hi:[1,0]
	v_pk_mul_f32 v[70:71], v[70:71], v[118:119] op_sel_hi:[1,0]
	v_pk_mul_f32 v[68:69], v[68:69], v[118:119] op_sel_hi:[1,0]
	v_pk_mul_f32 v[66:67], v[66:67], v[118:119] op_sel_hi:[1,0]
	v_pk_mul_f32 v[64:65], v[64:65], v[118:119] op_sel_hi:[1,0]
	v_pk_mul_f32 v[62:63], v[62:63], v[118:119] op_sel_hi:[1,0]
	v_pk_mul_f32 v[60:61], v[60:61], v[118:119] op_sel_hi:[1,0]
	v_pk_mul_f32 v[58:59], v[58:59], v[118:119] op_sel_hi:[1,0]
	v_pk_mul_f32 v[56:57], v[56:57], v[118:119] op_sel_hi:[1,0]
	v_pk_mul_f32 v[54:55], v[54:55], v[118:119] op_sel_hi:[1,0]
	v_pk_mul_f32 v[52:53], v[52:53], v[118:119] op_sel_hi:[1,0]
	v_pk_mul_f32 v[50:51], v[50:51], v[118:119] op_sel_hi:[1,0]
	v_pk_mul_f32 v[48:49], v[48:49], v[118:119] op_sel_hi:[1,0]
	v_mov_b32_e32 v118, v119
	v_cmp_lt_f32_e32 vcc, 0xdf0ac723, v118
	s_nop 1
	v_cndmask_b32_e32 v250, 0, v118, vcc
	v_sub_f32_e32 v251, v250, v248
	v_mov_b32_e32 v248, v250
	v_sub_f32_e32 v80, v80, v251
	v_sub_f32_e32 v81, v81, v251
	v_sub_f32_e32 v82, v82, v251
	v_sub_f32_e32 v83, v83, v251
	v_sub_f32_e32 v84, v84, v251
	v_sub_f32_e32 v85, v85, v251
	v_sub_f32_e32 v86, v86, v251
	v_sub_f32_e32 v87, v87, v251
	v_sub_f32_e32 v88, v88, v251
	v_sub_f32_e32 v89, v89, v251
	v_sub_f32_e32 v90, v90, v251
	v_sub_f32_e32 v91, v91, v251
	v_sub_f32_e32 v92, v92, v251
	v_sub_f32_e32 v93, v93, v251
	v_sub_f32_e32 v94, v94, v251
	v_sub_f32_e32 v95, v95, v251
.LBB0_834:
	v_exp_f32_e32 v119, v80
	v_exp_f32_e32 v120, v81
	v_exp_f32_e32 v121, v82
	v_exp_f32_e32 v122, v83
	v_add_f32_e32 v80, v120, v119
	v_add_f32_e32 v80, v121, v80
	v_add_f32_e32 v123, v122, v80
	v_exp_f32_e32 v124, v84
	v_exp_f32_e32 v125, v85
	v_exp_f32_e32 v126, v86
	v_exp_f32_e32 v127, v87
	v_exp_f32_e32 v144, v88
	v_exp_f32_e32 v145, v89
	v_exp_f32_e32 v146, v90
	v_exp_f32_e32 v147, v91
	v_exp_f32_e32 v154, v92
	v_exp_f32_e32 v156, v93
	v_add3_u32 v80, s14, v15, v174
	v_add_u32_e32 v88, 0x2000, v80
	ds_read2_b64 v[80:83], v88 offset0:136 offset1:138
	v_exp_f32_e32 v157, v94
	v_exp_f32_e32 v158, v95
	v_cvt_pk_bf16_f32 v84, v119, v120
	v_cvt_pk_bf16_f32 v85, v121, v122
	v_cvt_pk_bf16_f32 v86, v124, v125
	v_cvt_pk_bf16_f32 v87, v126, v127
	ds_read2_b64 v[88:91], v88 offset0:140 offset1:142
	v_add3_u32 v92, s14, v176, v174
	s_waitcnt lgkmcnt(1)
	v_mfma_f32_32x32x16_bf16 v[48:63], v[80:83], v[84:87], v[48:63]
	v_add_u32_e32 v119, 0x2000, v92
	ds_read2_b64 v[92:95], v119 offset0:136 offset1:138
	v_cvt_pk_bf16_f32 v80, v144, v145
	v_cvt_pk_bf16_f32 v81, v146, v147
	v_cvt_pk_bf16_f32 v82, v154, v156
	v_cvt_pk_bf16_f32 v83, v157, v158
	s_waitcnt lgkmcnt(0)
	v_mfma_f32_32x32x16_bf16 v[64:79], v[92:95], v[84:87], v[64:79]
	v_mfma_f32_32x32x16_bf16 v[48:63], v[88:91], v[80:83], v[48:63]
	v_add_f32_e32 v88, v124, v123
	v_add_f32_e32 v88, v125, v88
	v_add_f32_e32 v88, v126, v88
	v_add_f32_e32 v88, v127, v88
	v_add_f32_e32 v88, v144, v88
	v_add_f32_e32 v120, v145, v88
	ds_read2_b64 v[88:91], v119 offset0:140 offset1:142
	s_waitcnt lgkmcnt(0)
	v_mfma_f32_32x32x16_bf16 v[64:79], v[88:91], v[80:83], v[64:79]
	v_add_f32_e32 v84, v146, v120
	v_add_f32_e32 v84, v147, v84
	v_add_f32_e32 v84, v154, v84
	v_add_f32_e32 v84, v156, v84
	v_add_f32_e32 v84, v157, v84
	v_add_f32_e32 v84, v158, v84
	v_add_f32_e32 v175, v175, v84

; DI float xhalf_max(float v) { unsigned a = __builtin_bit_cast(unsigned, v), b = a; swap32(a, b); return fmaxf(__builtin_bit_cast(float, a), __builtin_bit_cast(float, b)); }
; DI float fexp2(float x) { return __builtin_amdgcn_exp2f(x); }
; template <int MODE>
; DI void nsa_tile(LAS const unsigned char* buf, const bf16x8 (&qf)[4], f32x16 (&o)[2], float& m, float& l, int kbase0, int t, bool lanesel, float slope2, int c, int hi) {
;     ...
;         float mx = max16(s);
;         mx = xhalf_max(mx);
;         if (__any(mx > m + 8.f)) {
;             const float mn = fmaxf(m, mx), alpha = fexp2(m - mn); m = mn; l *= alpha;
;             o[0] = o[0] * alpha; o[1] = o[1] * alpha;
;         }
;         float ps = 0.f;
; #pragma unroll
;         for (int i = 0; i < 16; ++i) { const float pv = fexp2(s[i] - m); s[i] = pv; ps += pv; }
;         l += ps;
.LBB0_850:
	v_max3_f32 v182, v112, v113, v114
	v_max3_f32 v183, v115, v116, v117
	v_max3_f32 v184, v118, v119, v120
	v_max3_f32 v185, v121, v122, v123
	s_nop 0
	v_max3_f32 v182, v182, v124, v125
	v_max3_f32 v183, v183, v126, v127
	s_nop 0
	v_max3_f32 v182, v182, v183, v184
	s_nop 0
	v_max3_f32 v182, v182, v185, v185
	s_nop 0
	v_mov_b32_e32 v183, v182
	s_nop 1
	v_permlane32_swap_b32 v182, v183
	s_nop 0
	v_max_f32_e32 v182, v182, v183
	v_add_f32_e32 v182, v182, v249
	v_add_f32_e32 v183, 0x41000000, v180
	v_cmp_gt_f32_e32 vcc, v182, v183
	s_cbranch_vccz .LBB0_852
	v_max_f32_e32 v182, v182, v182
	v_max_f32_e32 v183, v180, v180
	v_max_f32_e32 v182, v183, v182
	v_sub_f32_e32 v180, v180, v182
	v_exp_f32_e32 v180, v180
	s_nop 0
	v_mul_f32_e32 v161, v161, v180
	v_pk_mul_f32 v[110:111], v[110:111], v[180:181] op_sel_hi:[1,0]
	v_pk_mul_f32 v[108:109], v[108:109], v[180:181] op_sel_hi:[1,0]
	v_pk_mul_f32 v[106:107], v[106:107], v[180:181] op_sel_hi:[1,0]
	v_pk_mul_f32 v[104:105], v[104:105], v[180:181] op_sel_hi:[1,0]
	v_pk_mul_f32 v[102:103], v[102:103], v[180:181] op_sel_hi:[1,0]
	v_pk_mul_f32 v[100:101], v[100:101], v[180:181] op_sel_hi:[1,0]
	v_pk_mul_f32 v[98:99], v[98:99], v[180:181] op_sel_hi:[1,0]
	v_pk_mul_f32 v[96:97], v[96:97], v[180:181] op_sel_hi:[1,0]
	v_pk_mul_f32 v[94:95], v[94:95], v[180:181] op_sel_hi:[1,0]
	v_pk_mul_f32 v[92:93], v[92:93], v[180:181] op_sel_hi:[1,0]
	v_pk_mul_f32 v[90:91], v[90:91], v[180:181] op_sel_hi:[1,0]
	v_pk_mul_f32 v[88:89], v[88:89], v[180:181] op_sel_hi:[1,0]
	v_pk_mul_f32 v[86:87], v[86:87], v[180:181] op_sel_hi:[1,0]
	v_pk_mul_f32 v[84:85], v[84:85], v[180:181] op_sel_hi:[1,0]
	v_pk_mul_f32 v[82:83], v[82:83], v[180:181] op_sel_hi:[1,0]
	v_pk_mul_f32 v[80:81], v[80:81], v[180:181] op_sel_hi:[1,0]
	v_mov_b32_e32 v180, v182
	v_cmp_lt_f32_e32 vcc, 0xdf0ac723, v180
	s_nop 1
	v_cndmask_b32_e32 v250, 0, v180, vcc
	v_sub_f32_e32 v251, v250, v249
	v_mov_b32_e32 v249, v250
	v_sub_f32_e32 v112, v112, v251
	v_sub_f32_e32 v113, v113, v251
	v_sub_f32_e32 v114, v114, v251
	v_sub_f32_e32 v115, v115, v251
	v_sub_f32_e32 v116, v116, v251
	v_sub_f32_e32 v117, v117, v251
	v_sub_f32_e32 v118, v118, v251
	v_sub_f32_e32 v119, v119, v251
	v_sub_f32_e32 v120, v120, v251
	v_sub_f32_e32 v121, v121, v251
	v_sub_f32_e32 v122, v122, v251
	v_sub_f32_e32 v123, v123, v251
	v_sub_f32_e32 v124, v124, v251
	v_sub_f32_e32 v125, v125, v251
	v_sub_f32_e32 v126, v126, v251
	v_sub_f32_e32 v127, v127, v251
.LBB0_852:
	v_exp_f32_e32 v182, v112
	v_exp_f32_e32 v183, v113
	v_exp_f32_e32 v184, v114
	v_exp_f32_e32 v185, v115
	v_add_f32_e32 v112, v183, v182
	v_add_f32_e32 v112, v184, v112
	v_add_f32_e32 v186, v185, v112
	v_exp_f32_e32 v187, v116
	v_exp_f32_e32 v188, v117
	v_exp_f32_e32 v189, v118
	v_exp_f32_e32 v190, v119
	v_exp_f32_e32 v191, v120
	v_exp_f32_e32 v192, v121
	v_exp_f32_e32 v193, v122
	v_exp_f32_e32 v194, v123
	v_mov_b32_e32 v112, v124
	v_add3_u32 v124, s10, v15, v174
	v_exp_f32_e32 v195, v112
	v_add_u32_e32 v120, 0x2000, v124
	v_exp_f32_e32 v196, v125
	ds_read2_b64 v[112:115], v120 offset0:128 offset1:130
	v_exp_f32_e32 v197, v126
	v_cvt_pk_bf16_f32 v116, v182, v183
	v_cvt_pk_bf16_f32 v117, v184, v185
	v_cvt_pk_bf16_f32 v118, v187, v188
	v_cvt_pk_bf16_f32 v119, v189, v190
	ds_read2_b64 v[120:123], v120 offset0:132 offset1:134
	s_waitcnt lgkmcnt(1)
	v_mfma_f32_32x32x16_bf16 v[96:111], v[112:115], v[116:119], v[96:111]
	v_exp_f32_e32 v182, v127
	v_add_u32_e32 v183, 0x3000, v124
	ds_read2_b64 v[124:127], v183 offset0:160 offset1:162
	v_cvt_pk_bf16_f32 v112, v191, v192
	v_cvt_pk_bf16_f32 v113, v193, v194
	v_cvt_pk_bf16_f32 v114, v195, v196
	v_cvt_pk_bf16_f32 v115, v197, v182
	s_waitcnt lgkmcnt(0)
	v_mfma_f32_32x32x16_bf16 v[80:95], v[124:127], v[116:119], v[80:95]
	v_mfma_f32_32x32x16_bf16 v[96:111], v[120:123], v[112:115], v[96:111]
	v_add_f32_e32 v120, v187, v186
	v_add_f32_e32 v120, v188, v120
	v_add_f32_e32 v120, v189, v120
	v_add_f32_e32 v120, v190, v120
	v_add_f32_e32 v120, v191, v120
	v_add_f32_e32 v184, v192, v120
	ds_read2_b64 v[120:123], v183 offset0:164 offset1:166
	s_waitcnt lgkmcnt(0)
	v_mfma_f32_32x32x16_bf16 v[80:95], v[120:123], v[112:115], v[80:95]
	v_add_f32_e32 v116, v193, v184
	v_add_f32_e32 v116, v194, v116
	v_add_f32_e32 v116, v195, v116
	v_add_f32_e32 v116, v196, v116
	v_add_f32_e32 v116, v197, v116
	v_add_f32_e32 v116, v182, v116
	v_add_f32_e32 v161, v161, v116

; DI float xhalf_max(float v) { unsigned a = __builtin_bit_cast(unsigned, v), b = a; swap32(a, b); return fmaxf(__builtin_bit_cast(float, a), __builtin_bit_cast(float, b)); }
; DI float fexp2(float x) { return __builtin_amdgcn_exp2f(x); }
; template <int MODE>
; DI void nsa_tile(LAS const unsigned char* buf, const bf16x8 (&qf)[4], f32x16 (&o)[2], float& m, float& l, int kbase0, int t, bool lanesel, float slope2, int c, int hi) {
;     ...
;         float mx = max16(s);
;         mx = xhalf_max(mx);
;         if (__any(mx > m + 8.f)) {
;             const float mn = fmaxf(m, mx), alpha = fexp2(m - mn); m = mn; l *= alpha;
;             o[0] = o[0] * alpha; o[1] = o[1] * alpha;
;         }
;         float ps = 0.f;
; #pragma unroll
;         for (int i = 0; i < 16; ++i) { const float pv = fexp2(s[i] - m); s[i] = pv; ps += pv; }
;         l += ps;
.LBB0_856:
	v_max3_f32 v181, v112, v113, v114
	v_max3_f32 v182, v115, v116, v117
	v_max3_f32 v183, v118, v119, v120
	v_max3_f32 v184, v121, v122, v123
	s_nop 0
	v_max3_f32 v181, v181, v124, v125
	v_max3_f32 v182, v182, v126, v127
	s_nop 0
	v_max3_f32 v181, v181, v182, v183
	s_nop 0
	v_max3_f32 v181, v181, v184, v184
	s_nop 0
	v_mov_b32_e32 v182, v181
	s_nop 1
	v_permlane32_swap_b32 v181, v182
	s_nop 0
	v_max_f32_e32 v181, v181, v182
	v_add_f32_e32 v181, v181, v249
	v_add_f32_e32 v182, 0x41000000, v180
	v_cmp_gt_f32_e32 vcc, v181, v182
	s_cbranch_vccz .LBB0_858
	v_max_f32_e32 v181, v181, v181
	v_max_f32_e32 v182, v180, v180
	v_max_f32_e32 v181, v182, v181
	v_sub_f32_e32 v180, v180, v181
	v_exp_f32_e32 v180, v180
	s_nop 0
	v_mul_f32_e32 v161, v161, v180
	v_pk_mul_f32 v[110:111], v[110:111], v[180:181] op_sel_hi:[1,0]
	v_pk_mul_f32 v[108:109], v[108:109], v[180:181] op_sel_hi:[1,0]
	v_pk_mul_f32 v[106:107], v[106:107], v[180:181] op_sel_hi:[1,0]
	v_pk_mul_f32 v[104:105], v[104:105], v[180:181] op_sel_hi:[1,0]
	v_pk_mul_f32 v[102:103], v[102:103], v[180:181] op_sel_hi:[1,0]
	v_pk_mul_f32 v[100:101], v[100:101], v[180:181] op_sel_hi:[1,0]
	v_pk_mul_f32 v[98:99], v[98:99], v[180:181] op_sel_hi:[1,0]
	v_pk_mul_f32 v[96:97], v[96:97], v[180:181] op_sel_hi:[1,0]
	v_pk_mul_f32 v[94:95], v[94:95], v[180:181] op_sel_hi:[1,0]
	v_pk_mul_f32 v[92:93], v[92:93], v[180:181] op_sel_hi:[1,0]
	v_pk_mul_f32 v[90:91], v[90:91], v[180:181] op_sel_hi:[1,0]
	v_pk_mul_f32 v[88:89], v[88:89], v[180:181] op_sel_hi:[1,0]
	v_pk_mul_f32 v[86:87], v[86:87], v[180:181] op_sel_hi:[1,0]
	v_pk_mul_f32 v[84:85], v[84:85], v[180:181] op_sel_hi:[1,0]
	v_pk_mul_f32 v[82:83], v[82:83], v[180:181] op_sel_hi:[1,0]
	v_pk_mul_f32 v[80:81], v[80:81], v[180:181] op_sel_hi:[1,0]
	v_mov_b32_e32 v180, v181
	v_cmp_lt_f32_e32 vcc, 0xdf0ac723, v180
	s_nop 1
	v_cndmask_b32_e32 v250, 0, v180, vcc
	v_sub_f32_e32 v251, v250, v249
	v_mov_b32_e32 v249, v250
	v_sub_f32_e32 v112, v112, v251
	v_sub_f32_e32 v113, v113, v251
	v_sub_f32_e32 v114, v114, v251
	v_sub_f32_e32 v115, v115, v251
	v_sub_f32_e32 v116, v116, v251
	v_sub_f32_e32 v117, v117, v251
	v_sub_f32_e32 v118, v118, v251
	v_sub_f32_e32 v119, v119, v251
	v_sub_f32_e32 v120, v120, v251
	v_sub_f32_e32 v121, v121, v251
	v_sub_f32_e32 v122, v122, v251
	v_sub_f32_e32 v123, v123, v251
	v_sub_f32_e32 v124, v124, v251
	v_sub_f32_e32 v125, v125, v251
	v_sub_f32_e32 v126, v126, v251
	v_sub_f32_e32 v127, v127, v251
.LBB0_858:
	v_exp_f32_e32 v181, v112
	v_exp_f32_e32 v182, v113
	v_exp_f32_e32 v183, v114
	v_exp_f32_e32 v184, v115
	v_add_f32_e32 v112, v182, v181
	v_add_f32_e32 v112, v183, v112
	v_add_f32_e32 v185, v184, v112
	v_exp_f32_e32 v186, v116
	v_exp_f32_e32 v187, v117
	v_exp_f32_e32 v188, v118
	v_exp_f32_e32 v189, v119
	v_exp_f32_e32 v190, v120
	v_exp_f32_e32 v191, v121
	v_exp_f32_e32 v192, v122
	v_exp_f32_e32 v193, v123
	v_exp_f32_e32 v194, v124
	v_exp_f32_e32 v195, v125
	v_add3_u32 v112, s10, v15, v174
	v_add_u32_e32 v120, 0x2000, v112
	ds_read2_b64 v[112:115], v120 offset0:136 offset1:138
	v_exp_f32_e32 v196, v126
	v_exp_f32_e32 v197, v127
	v_cvt_pk_bf16_f32 v116, v181, v182
	v_cvt_pk_bf16_f32 v117, v183, v184
	v_cvt_pk_bf16_f32 v118, v186, v187
	v_cvt_pk_bf16_f32 v119, v188, v189
	ds_read2_b64 v[120:123], v120 offset0:140 offset1:142
	v_add3_u32 v124, s10, v176, v174
	s_waitcnt lgkmcnt(1)
	v_mfma_f32_32x32x16_bf16 v[96:111], v[112:115], v[116:119], v[96:111]
	v_add_u32_e32 v181, 0x2000, v124
	ds_read2_b64 v[124:127], v181 offset0:136 offset1:138
	v_cvt_pk_bf16_f32 v112, v190, v191
	v_cvt_pk_bf16_f32 v113, v192, v193
	v_cvt_pk_bf16_f32 v114, v194, v195
	v_cvt_pk_bf16_f32 v115, v196, v197
	s_waitcnt lgkmcnt(0)
	v_mfma_f32_32x32x16_bf16 v[80:95], v[124:127], v[116:119], v[80:95]
	v_mfma_f32_32x32x16_bf16 v[96:111], v[120:123], v[112:115], v[96:111]
	v_add_f32_e32 v120, v186, v185
	v_add_f32_e32 v120, v187, v120
	v_add_f32_e32 v120, v188, v120
	v_add_f32_e32 v120, v189, v120
	v_add_f32_e32 v120, v190, v120
	v_add_f32_e32 v182, v191, v120
	ds_read2_b64 v[120:123], v181 offset0:140 offset1:142
	s_waitcnt lgkmcnt(0)
	v_mfma_f32_32x32x16_bf16 v[80:95], v[120:123], v[112:115], v[80:95]
	v_add_f32_e32 v116, v192, v182
	v_add_f32_e32 v116, v193, v116
	v_add_f32_e32 v116, v194, v116
	v_add_f32_e32 v116, v195, v116
	v_add_f32_e32 v116, v196, v116
	v_add_f32_e32 v116, v197, v116
	v_add_f32_e32 v161, v161, v116

; __global__ void __launch_bounds__(NTHREADS, 2) fwd_megakernel(Params p) {
;     extern __shared__ __attribute__((aligned(16))) unsigned char dyn_lds[];
	.amdhsa_kernel _Z14fwd_megakernel6Params
		.amdhsa_group_segment_fixed_size 0
		.amdhsa_private_segment_fixed_size 0
		.amdhsa_kernarg_size 432
		.amdhsa_user_sgpr_count 2
		.amdhsa_user_sgpr_dispatch_ptr 0
		.amdhsa_user_sgpr_queue_ptr 0
		.amdhsa_user_sgpr_kernarg_segment_ptr 1
		.amdhsa_user_sgpr_dispatch_id 0
		.amdhsa_user_sgpr_kernarg_preload_length 0
		.amdhsa_user_sgpr_kernarg_preload_offset 0
		.amdhsa_user_sgpr_private_segment_size 0
		.amdhsa_uses_dynamic_stack 0
		.amdhsa_enable_private_segment 0
		.amdhsa_system_sgpr_workgroup_id_x 1
		.amdhsa_system_sgpr_workgroup_id_y 0
		.amdhsa_system_sgpr_workgroup_id_z 0
		.amdhsa_system_sgpr_workgroup_info 0
		.amdhsa_system_vgpr_workitem_id 2
		.amdhsa_next_free_vgpr 256
		.amdhsa_next_free_sgpr 102
		.amdhsa_accum_offset 256
		.amdhsa_reserve_vcc 1
		.amdhsa_float_round_mode_32 0
		.amdhsa_float_round_mode_16_64 0
		.amdhsa_float_denorm_mode_32 3
		.amdhsa_float_denorm_mode_16_64 3
		.amdhsa_dx10_clamp 1
		.amdhsa_ieee_mode 1
		.amdhsa_fp16_overflow 0
		.amdhsa_tg_split 0
		.amdhsa_exception_fp_ieee_invalid_op 0
		.amdhsa_exception_fp_denorm_src 0
		.amdhsa_exception_fp_ieee_div_zero 0
		.amdhsa_exception_fp_ieee_overflow 0
		.amdhsa_exception_fp_ieee_underflow 0
		.amdhsa_exception_fp_ieee_inexact 0
		.amdhsa_exception_int_div_zero 0
	.end_amdhsa_kernel

; __global__ void __launch_bounds__(NTHREADS, 2) fwd_megakernel(Params p) {
;     extern __shared__ __attribute__((aligned(16))) unsigned char dyn_lds[];
amdhsa.kernels:
  - .agpr_count:     0
    .args:
      - .offset:         0
        .size:           176
        .value_kind:     by_value
      - .offset:         176
        .size:           4
        .value_kind:     hidden_block_count_x
      - .offset:         180
        .size:           4
        .value_kind:     hidden_block_count_y
      - .offset:         184
        .size:           4
        .value_kind:     hidden_block_count_z
      - .offset:         188
        .size:           2
        .value_kind:     hidden_group_size_x
      - .offset:         190
        .size:           2
        .value_kind:     hidden_group_size_y
      - .offset:         192
        .size:           2
        .value_kind:     hidden_group_size_z
      - .offset:         194
        .size:           2
        .value_kind:     hidden_remainder_x
      - .offset:         196
        .size:           2
        .value_kind:     hidden_remainder_y
      - .offset:         198
        .size:           2
        .value_kind:     hidden_remainder_z
      - .offset:         216
        .size:           8
        .value_kind:     hidden_global_offset_x
      - .offset:         224
        .size:           8
        .value_kind:     hidden_global_offset_y
      - .offset:         232
        .size:           8
        .value_kind:     hidden_global_offset_z
      - .offset:         240
        .size:           2
        .value_kind:     hidden_grid_dims
      - .offset:         264
        .size:           8
        .value_kind:     hidden_multigrid_sync_arg
      - .offset:         296
        .size:           4
        .value_kind:     hidden_dynamic_lds_size
    .group_segment_fixed_size: 0
    .kernarg_segment_align: 8
    .kernarg_segment_size: 432
    .language:       OpenCL C
    .language_version:
      - 2
      - 0
    .max_flat_workgroup_size: 512
    .name:           _Z14fwd_megakernel6Params
    .private_segment_fixed_size: 0
    .sgpr_count:     108
    .sgpr_spill_count: 36
    .symbol:         _Z14fwd_megakernel6Params.kd
    .uniform_work_group_size: 1
    .uses_dynamic_stack: false
    .vgpr_count:     256
    .vgpr_spill_count: 0
    .wavefront_size: 64
